# grid barriers: L1 invalidate issued at arrival (overlaps the wait) instead of after the release is observed
# speedup vs baseline: 1.0136x; 1.0136x over previous
; __device__ __forceinline__ unsigned xb_add(unsigned* p, unsigned v) { return __hip_atomic_fetch_add(p, v, __ATOMIC_RELAXED, __HIP_MEMORY_SCOPE_AGENT); }
; __device__ __forceinline__ void xcd_barrier(const XcdBarrier& b) {
;     ...
;     if (threadIdx.x == 0) {
;         unsigned* bar = b.bar;
;         __builtin_amdgcn_s_waitcnt(0);
;         unsigned nloc = b.st[0], nx = b.st[1];
;         if (nloc == 0u) { xcd_barrier_complete(bar, b.x, nloc, nx); b.st[0] = nloc; b.st[1] = nx; }
;         const unsigned old = xb_add(&bar[XB_XSUB(b.x)], 1u);
.LBB0_336:
	s_mov_b64 s[6:7], exec
	s_lshl_b32 s2, s90, 8
	v_mbcnt_lo_u32_b32 v1, s6, 0
	s_add_u32 s4, s96, s2
	v_mbcnt_hi_u32_b32 v1, s7, v1
	s_addc_u32 s5, s97, 0
	v_cmp_eq_u32_e32 vcc, 0, v1
	s_and_saveexec_b64 s[10:11], vcc
	s_cbranch_execz .LBB0_338
	s_bcnt1_i32_b64 s2, s[6:7]
	v_mov_b32_e32 v3, 0x1000
	v_mov_b32_e32 v4, s2
	buffer_inv sc1
	global_atomic_add v3, v3, v4, s[4:5] offset:1024 sc0

; __device__ __forceinline__ unsigned xb_ld(unsigned* p)              { return __hip_atomic_load(p, __ATOMIC_RELAXED, __HIP_MEMORY_SCOPE_AGENT); }
; #define XB_SPIN(cond, bar) do { unsigned _sp = 0; while (cond) { __builtin_amdgcn_s_sleep(1); \
;     if ((++_sp & 255u) == 0u) { if (xb_ld(&(bar)[XB_TMO])) break; if (_sp > XB_SPIN_CAP) { atomicAdd(&(bar)[XB_TMO], 1u); break; } } } } while (0)
; __device__ __forceinline__ void xcd_barrier(const XcdBarrier& b) {
;     ...
;             XB_SPIN(xb_ld(&bar[XB_XGEN(b.x)]) == gen, bar);
;             __builtin_amdgcn_fence(__ATOMIC_ACQUIRE, "agent");
;             asm volatile("s_waitcnt vmcnt(0)" ::: "memory");
.LBB0_351:
	s_or_b64 exec, exec, s[10:11]
	s_waitcnt vmcnt(0)
	s_waitcnt vmcnt(0)

; __device__ __forceinline__ unsigned xb_add(unsigned* p, unsigned v) { return __hip_atomic_fetch_add(p, v, __ATOMIC_RELAXED, __HIP_MEMORY_SCOPE_AGENT); }
; __device__ __forceinline__ void xcd_barrier(const XcdBarrier& b) {
;     ...
;             __builtin_amdgcn_fence(__ATOMIC_ACQUIRE, "agent");
;             xb_add(&bar[XB_XGEN(b.x)], 1u);
.LBB0_369:
	s_or_b64 exec, exec, s[6:7]
	s_mov_b64 s[6:7], exec
	v_mbcnt_lo_u32_b32 v0, s6, 0
	v_mbcnt_hi_u32_b32 v0, s7, v0
	v_cmp_eq_u32_e32 vcc, 0, v0
	s_waitcnt vmcnt(0)
	s_and_saveexec_b64 s[10:11], vcc
	s_cbranch_execz .LBB0_371
	s_bcnt1_i32_b64 s2, s[6:7]
	v_mov_b32_e32 v0, 0x2000
	v_mov_b32_e32 v1, s2
	global_atomic_add v0, v1, s[4:5] offset:1024

; __device__ __forceinline__ unsigned xb_add(unsigned* p, unsigned v) { return __hip_atomic_fetch_add(p, v, __ATOMIC_RELAXED, __HIP_MEMORY_SCOPE_AGENT); }
; __device__ __forceinline__ void xcd_barrier(const XcdBarrier& b) {
;     ...
;     if (threadIdx.x == 0) {
;         unsigned* bar = b.bar;
;         __builtin_amdgcn_s_waitcnt(0);
;         unsigned nloc = b.st[0], nx = b.st[1];
;         if (nloc == 0u) { xcd_barrier_complete(bar, b.x, nloc, nx); b.st[0] = nloc; b.st[1] = nx; }
;         const unsigned old = xb_add(&bar[XB_XSUB(b.x)], 1u);
.LBB0_462:
	s_mov_b64 s[6:7], exec
	s_lshl_b32 s2, s90, 8
	v_mbcnt_lo_u32_b32 v1, s6, 0
	s_add_u32 s4, s96, s2
	v_mbcnt_hi_u32_b32 v1, s7, v1
	s_addc_u32 s5, s97, 0
	v_cmp_eq_u32_e32 vcc, 0, v1
	s_and_saveexec_b64 s[8:9], vcc
	s_cbranch_execz .LBB0_464
	s_bcnt1_i32_b64 s2, s[6:7]
	v_mov_b32_e32 v3, 0x1000
	v_mov_b32_e32 v4, s2
	buffer_inv sc1
	global_atomic_add v3, v3, v4, s[4:5] offset:1024 sc0

; __device__ __forceinline__ unsigned xb_ld(unsigned* p)              { return __hip_atomic_load(p, __ATOMIC_RELAXED, __HIP_MEMORY_SCOPE_AGENT); }
; #define XB_SPIN(cond, bar) do { unsigned _sp = 0; while (cond) { __builtin_amdgcn_s_sleep(1); \
;     if ((++_sp & 255u) == 0u) { if (xb_ld(&(bar)[XB_TMO])) break; if (_sp > XB_SPIN_CAP) { atomicAdd(&(bar)[XB_TMO], 1u); break; } } } } while (0)
; __device__ __forceinline__ void xcd_barrier(const XcdBarrier& b) {
;     ...
;             XB_SPIN(xb_ld(&bar[XB_XGEN(b.x)]) == gen, bar);
;             __builtin_amdgcn_fence(__ATOMIC_ACQUIRE, "agent");
;             asm volatile("s_waitcnt vmcnt(0)" ::: "memory");
.LBB0_477:
	s_or_b64 exec, exec, s[8:9]
	s_waitcnt vmcnt(0)
	s_waitcnt vmcnt(0)

; __device__ __forceinline__ unsigned xb_add(unsigned* p, unsigned v) { return __hip_atomic_fetch_add(p, v, __ATOMIC_RELAXED, __HIP_MEMORY_SCOPE_AGENT); }
; __device__ __forceinline__ void xcd_barrier(const XcdBarrier& b) {
;     ...
;             __builtin_amdgcn_fence(__ATOMIC_ACQUIRE, "agent");
;             xb_add(&bar[XB_XGEN(b.x)], 1u);
.LBB0_495:
	s_or_b64 exec, exec, s[8:9]
	s_mov_b64 s[8:9], exec
	v_mbcnt_lo_u32_b32 v0, s8, 0
	v_mbcnt_hi_u32_b32 v0, s9, v0
	v_cmp_eq_u32_e32 vcc, 0, v0
	s_waitcnt vmcnt(0)
	s_and_saveexec_b64 s[10:11], vcc
	s_cbranch_execz .LBB0_497
	s_bcnt1_i32_b64 s2, s[8:9]
	v_mov_b32_e32 v0, 0x2000
	v_mov_b32_e32 v1, s2
	global_atomic_add v0, v1, s[4:5] offset:1024

; __device__ __forceinline__ unsigned xb_add(unsigned* p, unsigned v) { return __hip_atomic_fetch_add(p, v, __ATOMIC_RELAXED, __HIP_MEMORY_SCOPE_AGENT); }
; __device__ __forceinline__ void xcd_barrier(const XcdBarrier& b) {
;     ...
;     if (threadIdx.x == 0) {
;         unsigned* bar = b.bar;
;         __builtin_amdgcn_s_waitcnt(0);
;         unsigned nloc = b.st[0], nx = b.st[1];
;         if (nloc == 0u) { xcd_barrier_complete(bar, b.x, nloc, nx); b.st[0] = nloc; b.st[1] = nx; }
;         const unsigned old = xb_add(&bar[XB_XSUB(b.x)], 1u);
.LBB0_698:
	s_mov_b64 s[8:9], exec
	s_lshl_b32 s0, s90, 8
	v_mbcnt_lo_u32_b32 v1, s8, 0
	s_add_u32 s6, s96, s0
	v_mbcnt_hi_u32_b32 v1, s9, v1
	s_addc_u32 s7, s97, 0
	v_cmp_eq_u32_e32 vcc, 0, v1
	s_and_saveexec_b64 s[10:11], vcc
	s_cbranch_execz .LBB0_700
	s_bcnt1_i32_b64 s0, s[8:9]
	v_mov_b32_e32 v3, 0x1000
	v_mov_b32_e32 v4, s0
	buffer_inv sc1
	global_atomic_add v3, v3, v4, s[6:7] offset:1024 sc0

; __device__ __forceinline__ unsigned xb_add(unsigned* p, unsigned v) { return __hip_atomic_fetch_add(p, v, __ATOMIC_RELAXED, __HIP_MEMORY_SCOPE_AGENT); }
; __device__ __forceinline__ void xcd_barrier(const XcdBarrier& b) {
;     ...
;             __builtin_amdgcn_fence(__ATOMIC_ACQUIRE, "agent");
;             xb_add(&bar[XB_XGEN(b.x)], 1u);
.LBB0_731:
	s_or_b64 exec, exec, s[10:11]
	s_mov_b64 s[10:11], exec
	v_mbcnt_lo_u32_b32 v0, s10, 0
	v_mbcnt_hi_u32_b32 v0, s11, v0
	v_cmp_eq_u32_e32 vcc, 0, v0
	s_waitcnt vmcnt(0)
	s_and_saveexec_b64 s[12:13], vcc
	s_cbranch_execz .LBB0_733
	s_bcnt1_i32_b64 s0, s[10:11]
	v_mov_b32_e32 v0, 0x2000
	v_mov_b32_e32 v1, s0
	global_atomic_add v0, v1, s[6:7] offset:1024

; __device__ __forceinline__ unsigned xb_add(unsigned* p, unsigned v) { return __hip_atomic_fetch_add(p, v, __ATOMIC_RELAXED, __HIP_MEMORY_SCOPE_AGENT); }
; __device__ __forceinline__ void xcd_barrier(const XcdBarrier& b) {
;     ...
;     if (threadIdx.x == 0) {
;         unsigned* bar = b.bar;
;         __builtin_amdgcn_s_waitcnt(0);
;         unsigned nloc = b.st[0], nx = b.st[1];
;         if (nloc == 0u) { xcd_barrier_complete(bar, b.x, nloc, nx); b.st[0] = nloc; b.st[1] = nx; }
;         const unsigned old = xb_add(&bar[XB_XSUB(b.x)], 1u);
.LBB0_789:
	s_mov_b64 s[8:9], exec
	s_lshl_b32 s2, s90, 8
	v_mbcnt_lo_u32_b32 v1, s8, 0
	s_add_u32 s4, s96, s2
	v_mbcnt_hi_u32_b32 v1, s9, v1
	s_addc_u32 s5, s97, 0
	v_cmp_eq_u32_e32 vcc, 0, v1
	s_and_saveexec_b64 s[10:11], vcc
	s_cbranch_execz .LBB0_791
	s_bcnt1_i32_b64 s2, s[8:9]
	v_mov_b32_e32 v3, 0x1000
	v_mov_b32_e32 v4, s2
	buffer_inv sc1
	global_atomic_add v3, v3, v4, s[4:5] offset:1024 sc0

; __device__ __forceinline__ unsigned xb_add(unsigned* p, unsigned v) { return __hip_atomic_fetch_add(p, v, __ATOMIC_RELAXED, __HIP_MEMORY_SCOPE_AGENT); }
; __device__ __forceinline__ void xcd_barrier(const XcdBarrier& b) {
;     ...
;             __builtin_amdgcn_fence(__ATOMIC_ACQUIRE, "agent");
;             xb_add(&bar[XB_XGEN(b.x)], 1u);
.LBB0_822:
	s_or_b64 exec, exec, s[10:11]
	s_mov_b64 s[10:11], exec
	v_mbcnt_lo_u32_b32 v0, s10, 0
	v_mbcnt_hi_u32_b32 v0, s11, v0
	v_cmp_eq_u32_e32 vcc, 0, v0
	s_waitcnt vmcnt(0)
	s_and_saveexec_b64 s[12:13], vcc
	s_cbranch_execz .LBB0_824
	s_bcnt1_i32_b64 s2, s[10:11]
	v_mov_b32_e32 v0, 0x2000
	v_mov_b32_e32 v1, s2
	global_atomic_add v0, v1, s[4:5] offset:1024

; __device__ __forceinline__ unsigned xb_add(unsigned* p, unsigned v) { return __hip_atomic_fetch_add(p, v, __ATOMIC_RELAXED, __HIP_MEMORY_SCOPE_AGENT); }
; __device__ __forceinline__ void xcd_barrier(const XcdBarrier& b) {
;     ...
;             __builtin_amdgcn_fence(__ATOMIC_ACQUIRE, "agent");
;             xb_add(&bar[XB_XGEN(b.x)], 1u);
.LBB0_904:
	s_or_b64 exec, exec, s[8:9]
	s_mov_b64 s[8:9], exec
	v_mbcnt_lo_u32_b32 v0, s8, 0
	v_mbcnt_hi_u32_b32 v0, s9, v0
	v_cmp_eq_u32_e32 vcc, 0, v0
	s_waitcnt vmcnt(0)
	s_and_saveexec_b64 s[12:13], vcc
	s_cbranch_execz .LBB0_906
	s_bcnt1_i32_b64 s2, s[8:9]
	v_mov_b32_e32 v0, 0x2000
	v_mov_b32_e32 v1, s2
	global_atomic_add v0, v1, s[4:5] offset:1024

; __device__ __forceinline__ unsigned xb_add(unsigned* p, unsigned v) { return __hip_atomic_fetch_add(p, v, __ATOMIC_RELAXED, __HIP_MEMORY_SCOPE_AGENT); }
; __device__ __forceinline__ void xcd_barrier(const XcdBarrier& b) {
;     ...
;             __builtin_amdgcn_fence(__ATOMIC_ACQUIRE, "agent");
;             xb_add(&bar[XB_XGEN(b.x)], 1u);
.LBB0_977:
	s_or_b64 exec, exec, s[6:7]
	s_mov_b64 s[6:7], exec
	v_mbcnt_lo_u32_b32 v0, s6, 0
	v_mbcnt_hi_u32_b32 v0, s7, v0
	v_cmp_eq_u32_e32 vcc, 0, v0
	s_waitcnt vmcnt(0)
	s_and_saveexec_b64 s[8:9], vcc
	s_cbranch_execz .LBB0_979
	s_bcnt1_i32_b64 s2, s[6:7]
	v_mov_b32_e32 v0, 0x2000
	v_mov_b32_e32 v1, s2
	global_atomic_add v0, v1, s[4:5] offset:1024
